# same code as the selective-nt version with the whole instruction stream shifted by 32 bytes (8 nops at entry): byte-placement trial
# speedup vs baseline: 1.0023x; 1.0023x over previous
; DI unsigned xb_add(unsigned* p, unsigned v) { return __hip_atomic_fetch_add(p, v, __ATOMIC_RELAXED, __HIP_MEMORY_SCOPE_AGENT); }
; DI unsigned xb_xcc_id() { return (unsigned)__builtin_amdgcn_s_getreg((3 << 11) | 20) & 0xFu; }
; __global__ void __launch_bounds__(256, 2) mega_kernel(KArgs ka) {
;   __shared__ __attribute__((aligned(16))) char smem[SMEM_BYTES];
;   __shared__ uint4 xb_words;
;   cg::grid_group grid = cg::this_grid();
;   const int tid = threadIdx.x;
;   unsigned* const bar = (unsigned*)(ka.ws + OFF_BAR);
;   if (tid == 0) xb_words = make_uint4(0u, 0u, 0u, 0u);
;   if (ka.ws == nullptr) grid.sync();
;   if (tid == 0) (void)xb_add(&((unsigned*)(ka.ws + OFF_BAR))[XB_XCNT(xb_xcc_id())], 1u);
_Z11mega_kernel5KArgs:
	s_nop 0
	s_nop 0
	s_nop 0
	s_nop 0
	s_nop 0
	s_nop 0
	s_nop 0
	s_nop 0
	s_load_dwordx2 s[96:97], s[0:1], 0xd0
	s_load_dwordx4 s[16:19], s[0:1], 0xc0
	s_add_u32 s4, s0, 0xd8
	v_and_b32_e32 v206, 0x3ff, v0
	s_mov_b32 s48, s2
	s_addc_u32 s5, s1, 0
	v_cmp_eq_u32_e64 s[92:93], 0, v206
	s_and_saveexec_b64 s[2:3], s[92:93]
	s_cbranch_execnz .LBB0_3
	s_or_b64 exec, exec, s[2:3]
	s_load_dword s49, s[0:1], 0xd8
	s_waitcnt lgkmcnt(0)
	s_cmp_lg_u64 s[96:97], 0
	s_cbranch_scc0 .LBB0_4
